# v55 state after sandbox loss: waitcnt moves, prefetch hoists, grid.sync removal
# baseline (speedup 1.0000x reference)
.LBB0_765:
	s_add_i32 s0, s20, 0xffffff00
	s_ashr_i32 s1, s0, 31
	s_lshr_b32 s1, s1, 29
	s_add_i32 s1, s0, s1
	s_ashr_i32 s3, s1, 3
	s_and_b32 s1, s1, -8
	s_sub_i32 s0, s0, s1
	v_writelane_b32 v254, s0, 62
	s_nop 0
	v_readlane_b32 s0, v254, 50
	v_readlane_b32 s1, v254, 51
	s_and_b64 s[0:1], s[0:1], exec
	v_writelane_b32 v254, s3, 58
	s_cselect_b32 s0, -1, s3
	v_writelane_b32 v254, s0, 56
	s_cmpk_lt_i32 s20, 0x140
	s_nop 0
	v_writelane_b32 v254, s1, 57
	s_cselect_b64 s[0:1], -1, 0
	v_writelane_b32 v255, s0, 11
	s_cmpk_gt_i32 s20, 0x13f
	s_nop 0
	v_writelane_b32 v255, s1, 12
	s_cbranch_scc1 .LBB0_841
	v_ashrrev_i32_e32 v1, 31, v8
	v_lshrrev_b32_e32 v1, 26, v1
	v_add_u32_e32 v1, v8, v1
	v_ashrrev_i32_e32 v9, 6, v1
	v_bfe_i32 v1, v8, 27, 1
	v_lshlrev_b32_e32 v0, 4, v8
	v_lshrrev_b32_e32 v1, 22, v1
	v_add_u32_e32 v1, v0, v1
	v_and_b32_e32 v1, 0xfffffc00, v1
	v_sub_u32_e32 v1, v0, v1
	v_lshrrev_b32_e32 v2, 4, v1
	s_bfe_i32 s0, s2, 0x80000
	v_bitop3_b32 v1, v2, v1, 32 bitop3:0x6c
	s_bfe_u32 s0, s0, 0x3000c
	v_ashrrev_i32_e32 v3, 31, v1
	s_add_i32 s0, s2, s0
	v_lshrrev_b32_e32 v3, 26, v3
	s_bfe_i32 s0, s0, 0x80000
	v_add_u32_e32 v3, v1, v3
	s_sext_i32_i16 s0, s0
	v_readlane_b32 s4, v254, 50
	v_lshlrev_b32_e32 v2, 3, v9
	v_ashrrev_i32_e32 v10, 6, v3
	v_and_b32_e32 v3, 0xc0, v3
	s_ashr_i32 s2, s0, 3
	v_readlane_b32 s5, v254, 51
	v_and_b32_e32 v2, -16, v2
	v_sub_u32_e32 v1, v1, v3
	v_mov_b32_e32 v158, 1
	s_and_b64 s[0:1], s[4:5], exec
	v_add_u32_e32 v2, v10, v2
	v_ashrrev_i16_sdwa v1, v158, sext(v1) dst_sel:DWORD dst_unused:UNUSED_PAD src0_sel:DWORD src1_sel:BYTE_0
	v_lshlrev_b32_e32 v4, 5, v9
	v_bfe_i32 v11, v1, 0, 16
	v_lshlrev_b32_e32 v1, 1, v2
	v_lshrrev_b32_e32 v3, 2, v2
	v_and_b32_e32 v5, 3, v10
	s_mov_b32 s1, 0xfffe0
	v_and_b32_e32 v4, 32, v4
	v_and_b32_e32 v1, 24, v1
	v_and_b32_e32 v3, 4, v3
	v_and_or_b32 v5, v2, s1, v5
	v_or3_b32 v1, v5, v3, v1
	v_add_lshl_u32 v3, v4, v11, 1
	v_add_u32_e32 v0, 0x2000, v0
	v_lshl_add_u32 v130, v1, 12, v3
	v_ashrrev_i32_e32 v1, 31, v0
	v_lshrrev_b32_e32 v1, 22, v1
	v_add_u32_e32 v1, v0, v1
	v_ashrrev_i32_e32 v12, 10, v1
	v_mul_i32_i24_e32 v1, 0x400, v12
	v_sub_u32_e32 v0, v0, v1
	v_lshrrev_b32_e32 v1, 4, v0
	v_bitop3_b32 v0, v1, v0, 32 bitop3:0x6c
	v_lshl_add_u32 v128, v2, 12, v3
	v_ashrrev_i32_e32 v2, 31, v0
	v_readlane_b32 s0, v254, 62
	v_lshrrev_b32_e32 v2, 26, v2
	s_cselect_b32 s0, s2, s0
	s_add_u32 s21, s78, 0x26340000
	v_lshlrev_b32_e32 v1, 3, v12
	v_add_u32_e32 v2, v0, v2
	s_addc_u32 s26, s79, 0
	v_and_b32_e32 v1, -16, v1
	v_ashrrev_i32_e32 v13, 6, v2
	s_add_u32 s27, s78, 0x3f00000
	v_add_u32_e32 v1, v13, v1
	v_and_b32_e32 v4, 3, v13
	s_addc_u32 s28, s79, 0
	s_ashr_i32 s2, s8, 6
	v_and_or_b32 v4, v1, s1, v4
	v_readlane_b32 s1, v254, 58
	s_ashr_i32 s9, s8, 8
	s_lshl_b32 s29, s2, 10
	s_lshl_b32 s1, s1, 8
	s_and_b64 s[4:5], s[4:5], exec
	s_cselect_b32 s4, 0, s1
	s_ashr_i32 s11, s10, 31
	s_ashr_i32 s5, s4, 31
	s_ashr_i32 s1, s0, 31
	s_lshl_b64 s[6:7], s[10:11], 20
	s_lshl_b64 s[4:5], s[4:5], 1
	s_lshl_b64 s[12:13], s[0:1], 20
	s_add_u32 s1, s27, s12
	s_addc_u32 s3, s28, s13
	v_and_b32_e32 v2, 0xc0, v2
	s_add_u32 s92, s1, s4
	v_sub_u32_e32 v0, v0, v2
	s_addc_u32 s93, s3, s5
	s_cmpk_lt_i32 s20, 0x40
	s_cbranch_scc0 .Lmf_b_O0
	s_and_b32 vcc_lo, s20, 7
	s_lshl_b32 vcc_lo, vcc_lo, 20
	s_lshr_b32 vcc_hi, s20, 3
	s_lshl_b32 vcc_hi, vcc_hi, 9
	s_add_i32 vcc_lo, vcc_lo, vcc_hi
	s_add_u32 s92, s27, vcc_lo
	s_addc_u32 s93, s28, 0
.Lmf_b_O0:
	s_add_i32 s30, s29, 16
	v_ashrrev_i16_sdwa v0, v158, sext(v0) dst_sel:DWORD dst_unused:UNUSED_PAD src0_sel:DWORD src1_sel:BYTE_0
	s_add_i32 m0, s30, 0x10000
	v_lshlrev_b32_e32 v3, 5, v12
	v_bfe_i32 v14, v0, 0, 16
	v_lshlrev_b32_e32 v0, 1, v1
	v_lshrrev_b32_e32 v2, 2, v1
	global_load_lds_dwordx4 v130, s[92:93]
	s_add_i32 m0, s30, 0x12000
	v_and_b32_e32 v3, 32, v3
	v_and_b32_e32 v0, 24, v0
	v_and_b32_e32 v2, 4, v2
	s_add_u32 s1, s21, s6
	v_or3_b32 v0, v4, v2, v0
	v_add_lshl_u32 v2, v3, v14, 1
	s_addc_u32 s3, s26, s7
	v_lshl_add_u32 v134, v0, 12, v2
	s_add_u32 s6, s92, 0x80000
	global_load_lds_dwordx4 v134, s[92:93]
	s_addc_u32 s7, s93, 0
	s_add_i32 m0, s30, 0x14000
	v_lshl_add_u32 v132, v1, 12, v2
	global_load_lds_dwordx4 v130, s[6:7]
	s_add_i32 m0, s30, 0x16000
	s_add_u32 s94, s1, s4
	s_addc_u32 s95, s3, s5
	s_cmpk_lt_i32 s20, 0x40
	s_cbranch_scc0 .Lmf_a_O0
	s_lshr_b32 vcc_lo, s20, 3
	s_lshl_b32 vcc_lo, vcc_lo, 9
	s_add_i32 vcc_lo, vcc_lo, 0x2000000
	s_add_u32 s94, s21, vcc_lo
	s_addc_u32 s95, s26, 0
.Lmf_a_O0:
	s_add_i32 s31, s30, 0x2000
	global_load_lds_dwordx4 v134, s[6:7]
	s_mov_b32 m0, s30
	s_add_u32 s4, s94, 0x80000
	global_load_lds_dwordx4 v128, s[94:95]
	s_mov_b32 m0, s31
	s_addc_u32 s5, s95, 0
	s_add_i32 s33, s30, 0x4000
	global_load_lds_dwordx4 v132, s[94:95]
	s_mov_b32 m0, s33
	s_add_i32 s52, s30, 0x6000
	global_load_lds_dwordx4 v128, s[4:5]
	s_mov_b32 m0, s52
	v_mov_b32_e32 v137, 0
	global_load_lds_dwordx4 v132, s[4:5]
	v_mov_b32_e32 v131, v137
	v_mov_b32_e32 v135, v137
	v_mov_b32_e32 v129, v137
	v_mov_b32_e32 v133, v137
	s_cmp_eq_u32 s9, 1
	s_mov_b32 s3, 0
	v_lshl_add_u64 v[6:7], s[92:93], 0, v[130:131]
	v_lshl_add_u64 v[4:5], s[92:93], 0, v[134:135]
	v_lshl_add_u64 v[0:1], s[94:95], 0, v[128:129]
	s_cselect_b64 s[4:5], -1, 0
	s_cmp_lg_u32 s9, 1
	v_lshl_add_u64 v[2:3], s[94:95], 0, v[132:133]
	s_cbranch_scc1 .LBB0_768
	s_barrier
.LBB0_768:
	s_add_u32 s6, s78, 0x15300000
	s_addc_u32 s7, s79, 0
	s_add_u32 s12, s78, 0x28440000
	s_addc_u32 s13, s79, 0
	s_add_u32 s36, s78, 0x90800
	s_addc_u32 s37, s79, 0
	s_add_u32 s16, s78, 0x29a40000
	s_addc_u32 s17, s79, 0
	s_add_u32 s34, s78, 0x29b48000
	s_addc_u32 s35, s79, 0
	v_bfe_u32 v16, v8, 4, 2
	s_add_u32 s38, s78, 0x94000
	v_and_b32_e32 v15, 15, v8
	v_lshlrev_b32_e32 v18, 4, v16
	v_lshlrev_b32_e32 v8, 2, v8
	s_mov_b64 s[72:73], 0x80
	s_addc_u32 s56, s79, 0
	s_and_b32 s57, s2, 3
	v_lshl_or_b32 v138, s9, 6, v15
	v_lshl_or_b32 v15, v15, 6, v18
	s_lshl_b32 s1, s9, 13
	v_and_b32_e32 v8, 32, v8
	s_add_i32 m0, s30, 0x18000
	v_lshl_add_u64 v[6:7], v[6:7], 0, s[72:73]
	v_bitop3_b32 v18, v15, s1, v8 bitop3:0xde
	s_lshl_b32 s1, s57, 12
	s_waitcnt vmcnt(2)
	s_barrier
	global_load_lds_dwordx4 v[6:7], off
	v_lshl_add_u64 v[4:5], v[4:5], 0, s[72:73]
	s_add_i32 m0, s30, 0x1a000
	s_add_i32 s58, s30, 0x8000
	s_add_i32 s59, s30, 0xa000
	global_load_lds_dwordx4 v[4:5], off
	v_lshl_add_u64 v[0:1], v[0:1], 0, s[72:73]
	s_mov_b32 m0, s58
	s_add_u32 s14, s92, 0x80080
	global_load_lds_dwordx4 v[0:1], off
	v_lshl_add_u64 v[0:1], v[2:3], 0, s[72:73]
	s_mov_b32 m0, s59
	s_addc_u32 s15, s93, 0
	global_load_lds_dwordx4 v[0:1], off
	s_add_i32 m0, s30, 0x1c000
	v_lshl_add_u64 v[0:1], s[14:15], 0, v[130:131]
	global_load_lds_dwordx4 v[0:1], off
	v_lshl_add_u64 v[0:1], s[14:15], 0, v[134:135]
	s_add_i32 m0, s30, 0x1e000
	s_cmpk_lt_u32 s8, 0x100
	global_load_lds_dwordx4 v[0:1], off
	v_or_b32_e32 v0, 16, v138
	v_ashrrev_i32_e32 v1, 31, v0
	v_lshlrev_b64 v[142:143], 13, v[0:1]
	v_or_b32_e32 v0, 32, v138
	v_ashrrev_i32_e32 v1, 31, v0
	v_lshlrev_b64 v[144:145], 13, v[0:1]
	v_or_b32_e32 v0, 48, v138
	v_ashrrev_i32_e32 v1, 31, v0
	v_lshlrev_b64 v[146:147], 13, v[0:1]
	v_lshlrev_b32_e32 v0, 15, v12
	v_and_b32_e32 v0, 0xffff0000, v0
	v_lshl_add_u32 v0, v13, 12, v0
	v_and_b32_e32 v1, 1, v12
	v_lshl_or_b32 v0, v1, 6, v0
	v_lshl_add_u32 v148, v14, 1, v0
	v_lshlrev_b32_e32 v0, 15, v9
	v_and_b32_e32 v0, 0xffff0000, v0
	s_waitcnt vmcnt(6)
	s_cselect_b64 s[76:77], -1, 0
	s_add_u32 s40, s78, 0x96000
	v_lshl_add_u32 v0, v10, 12, v0
	v_and_b32_e32 v1, 1, v9
	v_lshlrev_b32_e32 v17, 3, v16
	v_bitop3_b32 v159, v15, s1, v8 bitop3:0xde
	v_ashrrev_i32_e32 v139, 31, v138
	s_addc_u32 s41, s79, 0
	v_lshl_or_b32 v0, v1, 6, v0
	s_add_i32 s60, 16, 0x10000
	s_add_i32 s61, 16, 0x14000
	v_readlane_b32 s14, v254, 56
	v_lshl_or_b32 v160, s57, 5, v17
	v_cmp_eq_u32_e64 s[8:9], 0, v16
	v_lshlrev_b64 v[140:141], 13, v[138:139]
	v_mov_b32_e32 v149, v137
	v_lshl_add_u32 v150, v11, 1, v0
	v_mov_b32_e32 v151, v137
	v_add_u32_e32 v139, s60, v159
	v_add_u32_e32 v161, s61, v159
	v_add_u32_e32 v162, 16, v18
	s_movk_i32 s62, 0x2100
	s_mov_b32 s63, 0x100000
	s_mov_b32 s64, 0x200000
	s_mov_b32 s65, 0x300000
	s_mov_b32 s66, 0x400000
	s_mov_b32 s67, 0x500000
	s_mov_b32 s74, 0x600000
	s_mov_b32 s75, 0x700000
	v_mov_b32_e32 v163, 0x358637bd
	v_mbcnt_hi_u32_b32 v164, -1, v185
	s_mov_b32 s2, s14
	s_mov_b32 s96, s3
	s_and_b32 vcc_lo, s20, 7
	s_lshr_b32 vcc_hi, s20, 3
	s_cmpk_lt_i32 s20, 0x40
	s_cselect_b32 s10, 32, s10
	s_cselect_b32 s0, vcc_lo, s0
	s_cselect_b32 s97, 4, s97
	s_cselect_b32 s2, vcc_hi, s2
	s_barrier
	v_readlane_b32 s15, v254, 57
	s_branch .LBB0_771

.LBB0_771:
	s_add_i32 s96, s96, 1
	s_mul_i32 s1, s96, s22
	s_add_i32 s1, s1, s20
	s_cmpk_lt_i32 s20, 0x40
	s_cselect_b32 vcc_lo, 0x100, 0
	s_cmpk_lt_i32 s1, 0x200
	s_cselect_b32 vcc_lo, vcc_lo, 0
	s_xor_b32 s1, s1, vcc_lo
	s_cmpk_lt_i32 s1, 0x100
	s_cselect_b64 s[80:81], -1, 0
	s_and_b64 s[14:15], s[80:81], exec
	s_cselect_b32 s14, s1, 0
	s_ashr_i32 s11, s14, 31
	s_lshr_b32 s11, s11, 29
	s_add_i32 s11, s14, s11
	s_and_b32 s15, s11, -8
	s_sub_i32 s24, s14, s15
	s_cmp_gt_i32 s24, -1
	s_mov_b64 s[14:15], -1
	s_cbranch_scc0 .LBB0_773
	s_lshl_b32 s25, s24, 5
	s_mov_b64 s[14:15], 0

.LBB0_1698:
	v_readlane_b32 s0, v255, 11
	v_readlane_b32 s1, v255, 12
	s_andn2_b64 vcc, exec, s[0:1]
	s_cbranch_vccnz .LBB0_1774
	v_ashrrev_i32_e32 v1, 31, v8
	v_lshrrev_b32_e32 v1, 26, v1
	v_add_u32_e32 v1, v8, v1
	v_ashrrev_i32_e32 v9, 6, v1
	v_bfe_i32 v1, v8, 27, 1
	v_lshlrev_b32_e32 v0, 4, v8
	v_lshrrev_b32_e32 v1, 22, v1
	v_add_u32_e32 v1, v0, v1
	v_and_b32_e32 v1, 0xfffffc00, v1
	v_sub_u32_e32 v1, v0, v1
	v_lshrrev_b32_e32 v2, 4, v1
	s_bfe_i32 s0, s3, 0x80000
	v_bitop3_b32 v1, v2, v1, 32 bitop3:0x6c
	s_bfe_u32 s0, s0, 0x3000c
	v_ashrrev_i32_e32 v3, 31, v1
	s_add_i32 s0, s3, s0
	v_lshrrev_b32_e32 v3, 26, v3
	s_bfe_i32 s0, s0, 0x80000
	v_add_u32_e32 v3, v1, v3
	s_sext_i32_i16 s0, s0
	v_readlane_b32 s8, v254, 50
	v_lshlrev_b32_e32 v2, 3, v9
	v_ashrrev_i32_e32 v10, 6, v3
	v_and_b32_e32 v3, 0xc0, v3
	s_ashr_i32 s3, s0, 3
	v_readlane_b32 s9, v254, 51
	v_and_b32_e32 v2, -16, v2
	v_sub_u32_e32 v1, v1, v3
	v_mov_b32_e32 v158, 1
	s_and_b64 s[0:1], s[8:9], exec
	v_add_u32_e32 v2, v10, v2
	v_ashrrev_i16_sdwa v1, v158, sext(v1) dst_sel:DWORD dst_unused:UNUSED_PAD src0_sel:DWORD src1_sel:BYTE_0
	v_lshlrev_b32_e32 v4, 5, v9
	v_bfe_i32 v11, v1, 0, 16
	v_lshlrev_b32_e32 v1, 1, v2
	v_lshrrev_b32_e32 v3, 2, v2
	v_and_b32_e32 v5, 3, v10
	s_mov_b32 s1, 0xfffe0
	v_and_b32_e32 v4, 32, v4
	v_and_b32_e32 v1, 24, v1
	v_and_b32_e32 v3, 4, v3
	v_and_or_b32 v5, v2, s1, v5
	v_or3_b32 v1, v5, v3, v1
	v_add_lshl_u32 v3, v4, v11, 1
	v_add_u32_e32 v0, 0x2000, v0
	v_lshl_add_u32 v130, v1, 12, v3
	v_ashrrev_i32_e32 v1, 31, v0
	v_lshrrev_b32_e32 v1, 22, v1
	v_add_u32_e32 v1, v0, v1
	v_ashrrev_i32_e32 v12, 10, v1
	v_mul_i32_i24_e32 v1, 0x400, v12
	v_sub_u32_e32 v0, v0, v1
	v_lshrrev_b32_e32 v1, 4, v0
	v_bitop3_b32 v0, v1, v0, 32 bitop3:0x6c
	v_lshl_add_u32 v128, v2, 12, v3
	v_ashrrev_i32_e32 v2, 31, v0
	v_readlane_b32 s0, v254, 62
	v_lshrrev_b32_e32 v2, 26, v2
	s_cselect_b32 s0, s3, s0
	s_add_u32 s21, s34, 0x26340000
	v_lshlrev_b32_e32 v1, 3, v12
	v_add_u32_e32 v2, v0, v2
	s_addc_u32 s24, s35, 0
	v_and_b32_e32 v1, -16, v1
	v_ashrrev_i32_e32 v13, 6, v2
	s_add_u32 s25, s34, 0xc700000
	v_add_u32_e32 v1, v13, v1
	v_and_b32_e32 v4, 3, v13
	s_addc_u32 s33, s35, 0
	s_ashr_i32 s3, s2, 6
	v_and_or_b32 v4, v1, s1, v4
	v_readlane_b32 s1, v254, 58
	s_ashr_i32 s6, s2, 8
	s_lshl_b32 s52, s3, 10
	s_lshl_b32 s1, s1, 8
	s_and_b64 s[8:9], s[8:9], exec
	s_cselect_b32 s8, 0, s1
	s_ashr_i32 s5, s4, 31
	s_ashr_i32 s9, s8, 31
	s_ashr_i32 s1, s0, 31
	s_lshl_b64 s[10:11], s[4:5], 20
	s_lshl_b64 s[12:13], s[8:9], 1
	s_lshl_b64 s[8:9], s[0:1], 20
	s_add_u32 s1, s25, s8
	s_addc_u32 s5, s33, s9
	v_and_b32_e32 v2, 0xc0, v2
	s_add_u32 s8, s1, s12
	v_sub_u32_e32 v0, v0, v2
	s_addc_u32 s9, s5, s13
	s_cmpk_lt_i32 s20, 0x40
	s_cbranch_scc0 .Lmf_b_O1
	s_and_b32 vcc_lo, s20, 7
	s_lshl_b32 vcc_lo, vcc_lo, 20
	s_lshr_b32 vcc_hi, s20, 3
	s_lshl_b32 vcc_hi, vcc_hi, 9
	s_add_i32 vcc_lo, vcc_lo, vcc_hi
	s_add_u32 s8, s25, vcc_lo
	s_addc_u32 s9, s33, 0
.Lmf_b_O1:
	s_add_i32 s53, s52, 16
	v_ashrrev_i16_sdwa v0, v158, sext(v0) dst_sel:DWORD dst_unused:UNUSED_PAD src0_sel:DWORD src1_sel:BYTE_0
	s_add_i32 m0, s53, 0x10000
	v_lshlrev_b32_e32 v3, 5, v12
	v_bfe_i32 v14, v0, 0, 16
	v_lshlrev_b32_e32 v0, 1, v1
	v_lshrrev_b32_e32 v2, 2, v1
	global_load_lds_dwordx4 v130, s[8:9]
	s_add_i32 m0, s53, 0x12000
	v_and_b32_e32 v3, 32, v3
	v_and_b32_e32 v0, 24, v0
	v_and_b32_e32 v2, 4, v2
	s_add_u32 s1, s21, s10
	v_or3_b32 v0, v4, v2, v0
	v_add_lshl_u32 v2, v3, v14, 1
	s_addc_u32 s5, s24, s11
	v_lshl_add_u32 v134, v0, 12, v2
	s_add_u32 s10, s8, 0x80000
	global_load_lds_dwordx4 v134, s[8:9]
	s_addc_u32 s11, s9, 0
	s_add_i32 m0, s53, 0x14000
	v_lshl_add_u32 v132, v1, 12, v2
	global_load_lds_dwordx4 v130, s[10:11]
	s_add_i32 m0, s53, 0x16000
	s_add_u32 s48, s1, s12
	s_addc_u32 s49, s5, s13
	s_cmpk_lt_i32 s20, 0x40
	s_cbranch_scc0 .Lmf_a_O1
	s_lshr_b32 vcc_lo, s20, 3
	s_lshl_b32 vcc_lo, vcc_lo, 9
	s_add_i32 vcc_lo, vcc_lo, 0x2000000
	s_add_u32 s48, s21, vcc_lo
	s_addc_u32 s49, s24, 0
.Lmf_a_O1:
	s_add_i32 s54, s53, 0x2000
	global_load_lds_dwordx4 v134, s[10:11]
	s_mov_b32 m0, s53
	s_add_u32 s10, s48, 0x80000
	global_load_lds_dwordx4 v128, s[48:49]
	s_mov_b32 m0, s54
	s_addc_u32 s11, s49, 0
	s_add_i32 s55, s53, 0x4000
	global_load_lds_dwordx4 v132, s[48:49]
	s_mov_b32 m0, s55
	s_add_i32 s56, s53, 0x6000
	global_load_lds_dwordx4 v128, s[10:11]
	s_mov_b32 m0, s56
	v_mov_b32_e32 v137, 0
	global_load_lds_dwordx4 v132, s[10:11]
	v_mov_b32_e32 v131, v137
	v_mov_b32_e32 v135, v137
	v_mov_b32_e32 v129, v137
	v_mov_b32_e32 v133, v137
	s_cmp_eq_u32 s6, 1
	s_mov_b32 s7, 0
	v_lshl_add_u64 v[6:7], s[8:9], 0, v[130:131]
	v_lshl_add_u64 v[4:5], s[8:9], 0, v[134:135]
	v_lshl_add_u64 v[0:1], s[48:49], 0, v[128:129]
	s_cselect_b64 s[10:11], -1, 0
	s_cmp_lg_u32 s6, 1
	v_lshl_add_u64 v[2:3], s[48:49], 0, v[132:133]
	s_cbranch_scc1 .LBB0_1701
	s_barrier
.LBB0_1701:
	s_add_u32 s12, s34, 0x15300000
	s_addc_u32 s13, s35, 0
	s_add_u32 s14, s34, 0x28440000
	s_addc_u32 s15, s35, 0
	s_add_u32 s57, s34, 0x92000
	s_addc_u32 s58, s35, 0
	s_add_u32 s16, s34, 0x29a40000
	s_addc_u32 s17, s35, 0
	s_add_u32 s26, s34, 0x29b48000
	s_addc_u32 s27, s35, 0
	s_add_u32 s59, s34, 0x99000
	s_mov_b64 s[28:29], 0x80
	s_addc_u32 s60, s35, 0
	s_and_b32 s61, s3, 3
	s_add_i32 m0, s53, 0x18000
	v_lshl_add_u64 v[6:7], v[6:7], 0, s[28:29]
	s_lshl_b32 s1, s6, 13
	s_lshl_b32 s3, s61, 12
	s_waitcnt vmcnt(2)
	s_barrier
	global_load_lds_dwordx4 v[6:7], off
	v_lshl_add_u64 v[4:5], v[4:5], 0, s[28:29]
	s_add_i32 m0, s53, 0x1a000
	s_add_i32 s62, s53, 0x8000
	s_add_i32 s63, s53, 0xa000
	global_load_lds_dwordx4 v[4:5], off
	v_lshl_add_u64 v[0:1], v[0:1], 0, s[28:29]
	s_mov_b32 m0, s62
	s_add_u32 s30, s8, 0x80080
	global_load_lds_dwordx4 v[0:1], off
	v_lshl_add_u64 v[0:1], v[2:3], 0, s[28:29]
	s_mov_b32 m0, s63
	s_addc_u32 s31, s9, 0
	global_load_lds_dwordx4 v[0:1], off
	s_add_i32 m0, s53, 0x1c000
	v_lshl_add_u64 v[0:1], s[30:31], 0, v[130:131]
	global_load_lds_dwordx4 v[0:1], off
	v_lshl_add_u64 v[0:1], s[30:31], 0, v[134:135]
	s_add_i32 m0, s53, 0x1e000
	s_cmpk_lt_u32 s2, 0x100
	global_load_lds_dwordx4 v[0:1], off
	v_bfe_u32 v1, v8, 4, 2
	v_and_b32_e32 v0, 15, v8
	v_lshlrev_b32_e32 v3, 4, v1
	v_lshl_or_b32 v138, s6, 6, v0
	v_lshl_or_b32 v0, v0, 6, v3
	v_lshlrev_b32_e32 v3, 2, v8
	v_and_b32_e32 v3, 32, v3
	v_bitop3_b32 v4, v0, s1, v3 bitop3:0xde
	v_bitop3_b32 v159, v0, s3, v3 bitop3:0xde
	v_or_b32_e32 v0, 16, v138
	v_lshlrev_b32_e32 v2, 3, v1
	v_cmp_eq_u32_e64 s[2:3], 0, v1
	v_ashrrev_i32_e32 v1, 31, v0
	v_lshlrev_b64 v[142:143], 13, v[0:1]
	v_or_b32_e32 v0, 32, v138
	v_ashrrev_i32_e32 v1, 31, v0
	v_lshlrev_b64 v[144:145], 13, v[0:1]
	v_or_b32_e32 v0, 48, v138
	v_ashrrev_i32_e32 v1, 31, v0
	v_lshlrev_b64 v[146:147], 13, v[0:1]
	v_lshlrev_b32_e32 v0, 15, v12
	v_and_b32_e32 v0, 0xffff0000, v0
	v_lshl_add_u32 v0, v13, 12, v0
	v_and_b32_e32 v1, 1, v12
	v_lshl_or_b32 v0, v1, 6, v0
	v_lshl_add_u32 v148, v14, 1, v0
	v_lshlrev_b32_e32 v0, 15, v9
	v_and_b32_e32 v0, 0xffff0000, v0
	s_waitcnt vmcnt(6)
	s_cselect_b64 s[30:31], -1, 0
	s_add_u32 s34, s34, 0x9b000
	v_lshl_add_u32 v0, v10, 12, v0
	v_and_b32_e32 v1, 1, v9
	v_ashrrev_i32_e32 v139, 31, v138
	s_addc_u32 s35, s35, 0
	v_lshl_or_b32 v0, v1, 6, v0
	s_add_i32 s64, 16, 0x10000
	s_add_i32 s65, 16, 0x14000
	v_readlane_b32 s36, v254, 56
	v_lshl_or_b32 v160, s61, 5, v2
	v_lshlrev_b64 v[140:141], 13, v[138:139]
	v_mov_b32_e32 v149, v137
	v_lshl_add_u32 v150, v11, 1, v0
	v_mov_b32_e32 v151, v137
	v_add_u32_e32 v139, s64, v159
	v_add_u32_e32 v161, s65, v159
	v_add_u32_e32 v162, 16, v4
	s_movk_i32 s66, 0x2100
	s_mov_b32 s67, 0x100000
	s_mov_b32 s72, 0x200000
	s_mov_b32 s73, 0x300000
	s_mov_b32 s74, 0x400000
	s_mov_b32 s75, 0x500000
	s_mov_b32 s76, 0x600000
	s_mov_b32 s77, 0x700000
	v_mov_b32_e32 v163, 0x358637bd
	v_mbcnt_hi_u32_b32 v164, -1, v185
	s_mov_b32 s6, s36
	s_mov_b32 s78, s7
	s_and_b32 vcc_lo, s20, 7
	s_lshr_b32 vcc_hi, s20, 3
	s_cmpk_lt_i32 s20, 0x40
	s_cselect_b32 s4, 32, s4
	s_cselect_b32 s0, vcc_lo, s0
	s_cselect_b32 s81, 4, s81
	s_cselect_b32 s6, vcc_hi, s6
	s_barrier
	v_readlane_b32 s37, v254, 57
	s_branch .LBB0_1704

.LBB0_1704:
	s_add_i32 s78, s78, 1
	s_mul_i32 s1, s78, s22
	s_add_i32 s1, s1, s20
	s_cmpk_lt_i32 s20, 0x40
	s_cselect_b32 vcc_lo, 0x100, 0
	s_cmpk_lt_i32 s1, 0x200
	s_cselect_b32 vcc_lo, vcc_lo, 0
	s_xor_b32 s1, s1, vcc_lo
	s_cmpk_lt_i32 s1, 0x100
	s_cselect_b64 s[36:37], -1, 0
	s_and_b64 s[38:39], s[36:37], exec
	s_cselect_b32 s38, s1, 0
	s_ashr_i32 s5, s38, 31
	s_lshr_b32 s5, s5, 29
	s_add_i32 s5, s38, s5
	s_and_b32 s39, s5, -8
	s_sub_i32 s40, s38, s39
	s_cmp_gt_i32 s40, -1
	s_mov_b64 s[38:39], -1
	s_cbranch_scc0 .LBB0_1706
	s_lshl_b32 s41, s40, 5
	s_mov_b64 s[38:39], 0
